# NA / ret_out item-top waits leave the previous item's two output stores in flight (counted vmcnt(2), placeholder loads for the first item)
# baseline (speedup 1.0000x reference)
.Lna_W:
	v_and_b32_e32 v0, 7, v195
	v_bfe_u32 v1, v195, 3, 5
	v_lshlrev_b32_e32 v2, 4, v0
	v_mad_u32_u24 v163, v1, s79, v2
	s_mul_i32 s14, s11, 0x1100
	v_add_u32_e32 v163, s14, v163
	v_and_b32_e32 v3, 63, v195
	v_and_b32_e32 v4, 3, v3
	v_lshlrev_b32_e32 v4, 4, v4
	v_bfe_u32 v123, v3, 2, 2
	v_lshrrev_b32_e32 v6, 4, v3
	v_mul_u32_u24_e32 v207, 0x3d0, v6
	v_lshl_add_u32 v207, v123, 6, v207
	v_add_u32_e32 v207, v207, v4
	s_and_b32 s14, s10, 1
	s_lshl_b32 s14, s14, 4
	s_lshr_b32 s15, s10, 1
	s_lshl_b32 s15, s15, 2
	s_add_i32 s14, s14, s15
	s_mulk_i32 s14, 0x3d0
	s_add_i32 s14, s14, 0xff00
	v_add_u32_e32 v207, s14, v207
	v_lshlrev_b32_e32 v7, 2, v195
	v_add_u32_e32 v122, 0x1f300, v7
	s_waitcnt vmcnt(2)
	s_and_saveexec_b64 s[34:35], s[2:3]
	ds_write_b32 v122, v161
	s_mov_b64 exec, s[34:35]
	ds_write_b64 v163, v[124:125] offset:0
	ds_write_b64 v163, v[126:127] offset:8
	ds_write_b64 v163, v[128:129] offset:8704
	ds_write_b64 v163, v[130:131] offset:8712
	ds_write_b64 v163, v[132:133] offset:17408
	ds_write_b64 v163, v[134:135] offset:17416
	ds_write_b64 v163, v[136:137] offset:26112
	ds_write_b64 v163, v[138:139] offset:26120
	s_cmp_gt_i32 s0, 8
	s_cbranch_scc0 .Lna_kwr_done
	ds_write_b64 v163, v[140:141] offset:34816
	ds_write_b64 v163, v[142:143] offset:34824
	s_cmp_gt_i32 s0, 10
	s_cbranch_scc0 .Lna_kwr_done
	ds_write_b64 v163, v[164:165] offset:43520
	ds_write_b64 v163, v[166:167] offset:43528
	s_cmp_gt_i32 s0, 12
	s_cbranch_scc0 .Lna_kwr_done
	ds_write_b64 v163, v[168:169] offset:52224
	ds_write_b64 v163, v[170:171] offset:52232
	s_cmp_gt_i32 s0, 14
	s_cbranch_scc0 .Lna_kwr_done
	ds_write_b64 v163, v[172:173] offset:60928
	ds_write_b64 v163, v[174:175] offset:60936

.Lna_first:
	global_load_dword v81, v[0:1], off
	global_load_dword v82, v[0:1], off offset:4
	s_branch .Lna_top

.LBB0_860:
	s_and_b32 s14, s97, 3
	s_lshl_b32 s4, s97, 5
	s_and_b32 vcc_lo, s4, 0xffffff80
	s_lshl_b32 s0, s14, 6
	v_lshrrev_b32_e32 v0, 3, v33
	v_and_b32_e32 v1, 7, v33
	v_lshlrev_b32_e32 v2, 4, v1
	v_lshl_add_u32 v146, v0, 9, v2
	v_add_u32_e32 v147, 0x8000, v146
	v_mad_u32_u24 v176, v0, s18, v2
	v_and_b32_e32 v3, 32, v0
	v_bfe_u32 v1, v0, 2, 1
	v_lshl_or_b32 v3, v1, 4, v3
	v_bfe_u32 v1, v0, 3, 2
	v_lshl_or_b32 v3, v1, 2, v3
	v_and_b32_e32 v1, 3, v0
	v_or_b32_e32 v3, v3, v1
	v_mul_u32_u24_e32 v3, 0x90, v3
	v_add_u32_e32 v178, v3, v2
	v_lshlrev_b32_e32 v248, 4, v33
	v_add_u32_e32 v249, 0x2000, v248
	v_lshrrev_b32_e32 v0, 4, v33
	v_and_b32_e32 v1, 15, v33
	v_lshlrev_b32_e32 v2, 4, v1
	v_add_u32_e32 v3, s0, v0
	v_mul_u32_u24_e32 v3, 0x28000, v3
	v_add_u32_e32 v206, v3, v2
	v_add_u32_e32 v207, 0x500000, v206
	v_bfe_u32 v1, v0, 2, 1
	v_lshlrev_b32_e32 v3, 4, v1
	v_bfe_u32 v1, v0, 3, 2
	v_lshl_or_b32 v3, v1, 2, v3
	v_and_b32_e32 v1, 3, v0
	v_or_b32_e32 v3, v3, v1
	v_mul_u32_u24_e32 v3, 0x110, v3
	v_add_u32_e32 v177, v3, v2
	v_readlane_b32 s6, v254, 17
	v_readlane_b32 s7, v254, 18
	s_lshl_b32 s4, vcc_lo, 9
	s_lshl_b32 s5, s14, 7
	s_add_u32 s4, s4, s5
	s_add_u32 s6, s6, s4
	s_addc_u32 s7, s7, 0
	v_readlane_b32 s4, v253, 54
	v_readlane_b32 s5, v253, 55
	s_lshl_b32 s8, vcc_lo, 1
	s_add_u32 s4, s4, s8
	s_addc_u32 s5, s5, 0
	v_readlane_b32 s8, v254, 6
	v_readlane_b32 s9, v254, 7
	s_lshl_b32 s15, s97, 14
	s_add_u32 s8, s8, s15
	s_addc_u32 s9, s9, 0
	v_readlane_b32 s98, v253, 5
	s_nop 1
	s_cmp_lg_u32 s97, s98
	s_cbranch_scc1 .Lro_have
	global_load_dwordx4 v[148:151], v146, s[6:7]
	global_load_dwordx4 v[152:155], v147, s[6:7]
	global_load_dwordx4 v[156:159], v206, s[4:5]
	global_load_dwordx4 v[160:163], v207, s[4:5]
	global_load_dwordx4 v[164:167], v248, s[8:9]
	global_load_dwordx4 v[168:171], v249, s[8:9]
	global_load_dword v250, v146, s[6:7]
	global_load_dword v251, v146, s[6:7] offset:4
.Lro_have:
	v_mov_b32_e32 v109, s0
	s_waitcnt vmcnt(2)
	ds_write_b64 v176, v[148:149]
	ds_write_b64 v176, v[150:151] offset:8
	ds_write_b64 v176, v[152:153] offset:8704
	ds_write_b64 v176, v[154:155] offset:8712
	ds_write_b128 v177, v[156:159] offset:17408
	ds_write_b128 v177, v[160:163] offset:26112
	ds_write_b128 v178, v[164:167] offset:34816
	ds_write_b128 v178, v[168:171] offset:44032
	v_mov_b32_e32 v0, s0
	v_mov_b32_e32 v1, 0
	s_branch .Lro_compute
